# WKV2 chunk walk: both record sets kept in flight (loop-top wait counted, decay copies moved before their set's next request)
# speedup vs baseline: 1.0034x; 1.0034x over previous
; __device__ __forceinline__ void ph_wkv2(const Params& p, int jl, int lane, int wave) {
;     ...
;         static_assert(WC_NCH % 2 == 1, "chunk loop unrolled by two plus one");
;         WC_LOAD(RA, rec); WC_LOAD(RB, rec + REC_BYTES);
;         v2u ypk = (v2u){0u, 0u};
;         for (int c = 0; c + 1 < WC_NCH; c += 2) { WC_STEP(RA, RB, c); WC_STEP(RB, RA, c + 1); }
.LBB0_132:
	s_waitcnt vmcnt(15)
	v_mfma_f32_16x16x16_bf16 v[146:149], v[102:103], v[32:33], 0
	v_cvt_pk_bf16_f32 v177, v144, v145
	v_cvt_pk_bf16_f32 v176, v142, v143
	v_cvt_pk_bf16_f32 v179, v124, v125
	v_cvt_pk_bf16_f32 v178, v122, v123
	v_cvt_pk_bf16_f32 v187, v120, v121
	s_nop 2
	v_pk_add_f32 v[148:149], v[148:149], 0 op_sel_hi:[1,0]
	v_pk_add_f32 v[146:147], v[146:147], 0 op_sel_hi:[1,0]
	v_cvt_pk_bf16_f32 v186, v118, v119
	v_cvt_pk_bf16_f32 v189, v116, v117
	v_mfma_f32_16x16x32_bf16 v[2:5], v[2:5], v[176:179], v[146:149]
	v_cvt_pk_bf16_f32 v188, v114, v115
	v_add_u32_e32 v94, -16, v174
	v_ashrrev_i32_e32 v95, 31, v94
	v_mfma_f32_16x16x32_bf16 v[2:5], v[10:13], v[186:189], v[2:5]
	v_lshlrev_b64 v[94:95], 11, v[94:95]
	v_lshl_add_u64 v[94:95], v[172:173], 0, v[94:95]
	global_store_dwordx2 v[94:95], v[30:31], off
	v_mfma_f32_16x16x16_bf16 v[102:105], v[104:105], v[32:33], 0
	s_mov_b32 s20, 0x46f9b000
	s_nop 2
	v_cvt_pk_bf16_f32 v31, v4, v5
	v_cvt_pk_bf16_f32 v30, v2, v3
	v_ashrrev_i32_e32 v175, 31, v174
	s_cmpk_gt_u32 s19, 0x7d
	v_mfma_f32_16x16x32_bf16 v[2:5], v[38:41], v[30:33], v[142:145]
	v_add_f32_e64 v104, v104, 0
	v_add_f32_e64 v105, v105, 0
	v_pk_add_f32 v[102:103], v[102:103], 0 op_sel_hi:[1,0]
	s_nop 1
	v_mfma_f32_16x16x32_bf16 v[10:13], v[46:49], v[176:179], v[102:105]
	s_nop 1
	v_mul_f32_e64 v144, v52, v4
	v_mul_f32_e64 v145, v53, v5
	v_pk_mul_f32 v[142:143], v[50:51], v[2:3]
	v_lshl_add_u64 v[176:177], s[0:1], 0, v[160:161]
	v_mfma_f32_16x16x32_bf16 v[2:5], v[26:29], v[30:33], v[122:125]
	v_lshl_add_u64 v[178:179], s[0:1], 0, v[0:1]
	v_cvt_pk_bf16_f32 v191, v144, v145
	v_cvt_pk_bf16_f32 v190, v142, v143
	v_mfma_f32_16x16x32_bf16 v[146:149], v[42:45], v[186:189], v[10:13]
	s_waitcnt vmcnt(1)
	v_mfma_f32_16x16x16_bf16 v[186:189], v[112:113], v[96:97], 0
	s_nop 1
	v_mul_f32_e64 v124, v36, v4
	v_mul_f32_e64 v125, v37, v5
	v_pk_mul_f32 v[122:123], v[34:35], v[2:3]
	v_cvt_pk_bf16_f32 v193, v124, v125
	v_mfma_f32_16x16x32_bf16 v[2:5], v[14:17], v[30:33], v[118:121]
	v_cvt_pk_bf16_f32 v192, v122, v123
	v_pk_add_f32 v[188:189], v[188:189], 0 op_sel_hi:[1,0]
	v_pk_add_f32 v[186:187], v[186:187], 0 op_sel_hi:[1,0]
	s_nop 4
	v_pk_mul_f32 v[120:121], v[24:25], v[4:5]
	v_pk_mul_f32 v[118:119], v[22:23], v[2:3]
	v_mfma_f32_16x16x32_bf16 v[2:5], v[6:9], v[30:33], v[114:117]
	v_lshl_add_u64 v[30:31], s[0:1], 0, v[152:153]
	v_add_co_u32_e32 v6, vcc, s20, v30
	s_mov_b32 s20, 0x46f9c000
	s_nop 0
	v_addc_co_u32_e32 v7, vcc, 0, v31, vcc
	s_nop 2
	v_pk_mul_f32 v[116:117], v[20:21], v[4:5]
	v_pk_mul_f32 v[114:115], v[18:19], v[2:3]
	global_load_dwordx4 v[2:5], v[6:7], off offset:1280
	global_load_dwordx4 v[10:13], v[6:7], off offset:2304
	global_load_dwordx4 v[46:49], v[6:7], off offset:3328
	v_add_co_u32_e32 v6, vcc, s20, v30
	s_mov_b32 s20, 0x46f9e000
	s_nop 0
	v_addc_co_u32_e32 v7, vcc, 0, v31, vcc
	v_add_co_u32_e32 v94, vcc, s29, v30
	global_load_dwordx4 v[42:45], v[6:7], off offset:256
	global_load_dwordx4 v[38:41], v[6:7], off offset:1280
	global_load_dwordx4 v[26:29], v[6:7], off offset:2304
	global_load_dwordx4 v[14:17], v[6:7], off offset:3328
	v_addc_co_u32_e32 v95, vcc, 0, v31, vcc
	v_add_co_u32_e32 v18, vcc, s20, v176
	global_load_dwordx4 v[6:9], v[94:95], off offset:256
	s_nop 0
	v_addc_co_u32_e32 v19, vcc, 0, v177, vcc
	global_load_dwordx4 v[50:53], v[18:19], off offset:256
	global_load_dwordx4 v[34:37], v[18:19], off offset:320
	global_load_dwordx4 v[22:25], v[18:19], off offset:384
	s_nop 0
	global_load_dwordx4 v[18:21], v[18:19], off offset:448
	v_add_co_u32_e32 v32, vcc, s29, v178
	v_cvt_pk_bf16_f32 v197, v120, v121
	s_nop 0
	v_addc_co_u32_e32 v33, vcc, 0, v179, vcc
	global_load_dwordx2 v[32:33], v[32:33], off offset:1280
	s_nop 0
	global_load_dwordx4 v[102:105], v[94:95], off offset:3328
	v_cndmask_b32_e64 v94, v146, v147, s[4:5]
	v_cndmask_b32_e64 v95, v148, v149, s[4:5]
	v_cvt_pk_bf16_f32 v196, v118, v119
	v_mov_b32_dpp v94, v94 quad_perm:[1,0,3,2] row_mask:0xf bank_mask:0xf bound_ctrl:1
	v_mov_b32_dpp v95, v95 quad_perm:[1,0,3,2] row_mask:0xf bank_mask:0xf bound_ctrl:1
	v_cndmask_b32_e64 v146, v94, v146, s[4:5]
	v_cndmask_b32_e64 v94, v147, v94, s[4:5]
	v_cndmask_b32_e64 v147, v95, v148, s[4:5]
	v_cndmask_b32_e64 v95, v149, v95, s[4:5]
	v_cndmask_b32_e64 v148, v146, v147, s[6:7]
	v_cndmask_b32_e64 v149, v94, v95, s[6:7]
	v_cvt_pk_bf16_f32 v199, v116, v117
	v_mov_b32_dpp v148, v148 quad_perm:[2,3,0,1] row_mask:0xf bank_mask:0xf bound_ctrl:1
	v_mov_b32_dpp v149, v149 quad_perm:[2,3,0,1] row_mask:0xf bank_mask:0xf bound_ctrl:1
	v_cndmask_b32_e64 v146, v148, v146, s[6:7]
	v_cndmask_b32_e64 v94, v149, v94, s[6:7]
	v_cndmask_b32_e64 v147, v147, v148, s[6:7]
	v_cndmask_b32_e64 v95, v95, v149, s[6:7]
	v_cvt_pk_bf16_f32 v95, v147, v95
	v_cvt_pk_bf16_f32 v94, v146, v94
	v_lshlrev_b64 v[146:147], 11, v[174:175]
	v_lshl_add_u64 v[146:147], v[172:173], 0, v[146:147]
	global_store_dwordx2 v[146:147], v[94:95], off
	v_mfma_f32_16x16x16_bf16 v[146:149], v[110:111], v[96:97], 0
	v_cvt_pk_bf16_f32 v198, v114, v115
	s_nop 6
	v_pk_add_f32 v[148:149], v[148:149], 0 op_sel_hi:[1,0]
	v_pk_add_f32 v[146:147], v[146:147], 0 op_sel_hi:[1,0]
	s_nop 1
	v_mfma_f32_16x16x32_bf16 v[146:149], v[54:57], v[190:193], v[146:149]
	v_mfma_f32_16x16x32_bf16 v[200:203], v[58:61], v[196:199], v[146:149]
	v_mfma_f32_16x16x32_bf16 v[146:149], v[62:65], v[190:193], v[186:189]
	v_mfma_f32_16x16x32_bf16 v[146:149], v[66:69], v[196:199], v[146:149]
	s_nop 5
	v_cvt_pk_bf16_f32 v95, v202, v203
	v_cvt_pk_bf16_f32 v94, v200, v201
	s_nop 1
	v_mfma_f32_16x16x32_bf16 v[142:145], v[70:73], v[94:97], v[142:145]
	v_mfma_f32_16x16x32_bf16 v[122:125], v[74:77], v[94:97], v[122:125]
	v_mfma_f32_16x16x32_bf16 v[118:121], v[78:81], v[94:97], v[118:121]
	v_mfma_f32_16x16x32_bf16 v[114:117], v[82:85], v[94:97], v[114:117]
	v_mov_b64_e32 v[86:87], v[138:139]
	v_mov_b64_e32 v[90:91], v[134:135]
	v_mov_b64_e32 v[98:99], v[130:131]
	v_mov_b64_e32 v[106:107], v[126:127]
	v_mov_b64_e32 v[88:89], v[140:141]
	v_mov_b64_e32 v[92:93], v[136:137]
	v_mov_b64_e32 v[100:101], v[132:133]
	v_mov_b64_e32 v[108:109], v[128:129]
	s_cbranch_scc1 .LBB0_134
; __device__ __forceinline__ void ph_wkv2(const Params& p, int jl, int lane, int wave) {
;     ...
;         static_assert(WC_NCH % 2 == 1, "chunk loop unrolled by two plus one");
;         WC_LOAD(RA, rec); WC_LOAD(RB, rec + REC_BYTES);
;         v2u ypk = (v2u){0u, 0u};
;         for (int c = 0; c + 1 < WC_NCH; c += 2) { WC_STEP(RA, RB, c); WC_STEP(RB, RA, c + 1); }
	v_add_co_u32_e32 v66, vcc, 0x46f9e000, v30
	s_nop 1
	v_addc_co_u32_e32 v67, vcc, 0, v31, vcc
	v_add_co_u32_e32 v82, vcc, 0x46f9f000, v30
	global_load_dwordx4 v[54:57], v[66:67], off offset:512
	global_load_dwordx4 v[58:61], v[66:67], off offset:1536
	global_load_dwordx4 v[62:65], v[66:67], off offset:2560
	s_nop 0
	global_load_dwordx4 v[66:69], v[66:67], off offset:3584
	v_addc_co_u32_e32 v83, vcc, 0, v31, vcc
	v_add_co_u32_e32 v94, vcc, 0x46fa0000, v176
	global_load_dwordx4 v[70:73], v[82:83], off offset:512
	global_load_dwordx4 v[74:77], v[82:83], off offset:1536
	global_load_dwordx4 v[78:81], v[82:83], off offset:2560
	s_nop 0
	global_load_dwordx4 v[82:85], v[82:83], off offset:3584
	v_addc_co_u32_e32 v95, vcc, 0, v177, vcc
	global_load_dwordx4 v[126:129], v[94:95], off offset:3584
	global_load_dwordx4 v[130:133], v[94:95], off offset:3648
	global_load_dwordx4 v[134:137], v[94:95], off offset:3712
	global_load_dwordx4 v[138:141], v[94:95], off offset:3776
	v_add_co_u32_e32 v94, vcc, 0x46fa0000, v178
	s_nop 1
	v_addc_co_u32_e32 v95, vcc, 0, v179, vcc
	v_add_co_u32_e32 v30, vcc, 0x46fa0000, v30
	s_nop 1
	v_addc_co_u32_e32 v31, vcc, 0, v31, vcc
	global_load_dwordx2 v[96:97], v[94:95], off offset:512
	global_load_dwordx4 v[110:113], v[30:31], off offset:2560
.LBB0_134:
	v_cndmask_b32_e64 v30, v146, v147, s[4:5]
	v_cndmask_b32_e64 v31, v148, v149, s[4:5]
	s_nop 4
	v_pk_mul_f32 v[114:115], v[86:87], v[114:115]
	v_mov_b32_dpp v30, v30 quad_perm:[1,0,3,2] row_mask:0xf bank_mask:0xf bound_ctrl:1
	v_mov_b32_dpp v31, v31 quad_perm:[1,0,3,2] row_mask:0xf bank_mask:0xf bound_ctrl:1
	v_cndmask_b32_e64 v86, v30, v146, s[4:5]
	v_cndmask_b32_e64 v30, v147, v30, s[4:5]
	v_cndmask_b32_e64 v87, v31, v148, s[4:5]
	v_cndmask_b32_e64 v31, v149, v31, s[4:5]
	v_pk_mul_f32 v[116:117], v[88:89], v[116:117]
	v_cndmask_b32_e64 v88, v86, v87, s[6:7]
	v_cndmask_b32_e64 v89, v30, v31, s[6:7]
	s_add_u32 s0, s0, 0x5a00
	v_mov_b32_dpp v88, v88 quad_perm:[2,3,0,1] row_mask:0xf bank_mask:0xf bound_ctrl:1
	v_mov_b32_dpp v89, v89 quad_perm:[2,3,0,1] row_mask:0xf bank_mask:0xf bound_ctrl:1
	v_cndmask_b32_e64 v86, v88, v86, s[6:7]
	v_cndmask_b32_e64 v30, v89, v30, s[6:7]
	v_cndmask_b32_e64 v87, v87, v88, s[6:7]
	v_cndmask_b32_e64 v31, v31, v89, s[6:7]
	s_addc_u32 s1, s1, 0
	s_add_i32 s20, s19, 3
	s_add_i32 s19, s19, 2
	v_pk_mul_f32 v[144:145], v[108:109], v[144:145]
	v_pk_mul_f32 v[142:143], v[106:107], v[142:143]
	v_pk_mul_f32 v[124:125], v[100:101], v[124:125]
	v_pk_mul_f32 v[122:123], v[98:99], v[122:123]
	v_pk_mul_f32 v[120:121], v[92:93], v[120:121]
	v_pk_mul_f32 v[118:119], v[90:91], v[118:119]
	v_cvt_pk_bf16_f32 v31, v87, v31
	v_cvt_pk_bf16_f32 v30, v86, v30
	s_cmpk_gt_u32 s20, 0x80
	v_add_u32_e32 v174, 32, v174
	s_cbranch_scc1 .LBB0_130
	s_branch .LBB0_132
